# both attention loops: rescale test on per-half partial row max (cross-half permlane only in the rare rescale path)
# speedup vs baseline: 1.0688x; 1.0087x over previous
.Ldg_nb0_2:
	v_max3_f32 v64, v66, v67, v68
	v_max3_f32 v64, v64, v69, v70
	v_max3_f32 v64, v64, v71, v72
	v_max3_f32 v64, v64, v73, v74
	v_max3_f32 v64, v64, v75, v76
	v_max3_f32 v64, v64, v77, v78
	v_max3_f32 v64, v64, v79, v80
	v_max_f32_e32 v64, v64, v81
	v_cmp_lt_f32_e32 vcc, s97, v64
	s_cbranch_vccnz .Ldg_rare0_2

.Ldg_nb1_3:
	v_max3_f32 v64, v236, v237, v238
	v_max3_f32 v64, v64, v239, v240
	v_max3_f32 v64, v64, v241, v242
	v_max3_f32 v64, v64, v243, v244
	v_max3_f32 v64, v64, v245, v246
	v_max3_f32 v64, v64, v247, v248
	v_max3_f32 v64, v64, v249, v250
	v_max_f32_e32 v64, v64, v251
	v_cmp_lt_f32_e32 vcc, s97, v64
	s_cbranch_vccnz .Ldg_rare1_3
	s_waitcnt lgkmcnt(3)
	v_mfma_f32_32x32x16_bf16 v[32:47], v[200:203], v[130:133], v[32:47]
	ds_read_b128 v[126:129], v195 offset:16384
	ds_read_b128 v[114:117], v195 offset:20480
	v_exp_f32_e32 v236, v236
	v_exp_f32_e32 v237, v237
	v_exp_f32_e32 v238, v238
	s_waitcnt lgkmcnt(4)
	v_mfma_f32_32x32x16_bf16 v[48:63], v[200:203], v[134:137], v[48:63]
	ds_read_b128 v[122:125], v196 offset:16384
	ds_read_b128 v[118:121], v196 offset:20480
	v_exp_f32_e32 v239, v239
	v_exp_f32_e32 v240, v240
	v_exp_f32_e32 v241, v241
	s_waitcnt lgkmcnt(5)
	v_mfma_f32_32x32x16_bf16 v[32:47], v[204:207], v[138:141], v[32:47]
	v_exp_f32_e32 v242, v242
	v_exp_f32_e32 v243, v243
	v_exp_f32_e32 v244, v244
	s_waitcnt lgkmcnt(4)
	v_mfma_f32_32x32x16_bf16 v[48:63], v[204:207], v[142:145], v[48:63]
	v_exp_f32_e32 v245, v245
	v_exp_f32_e32 v246, v246
	v_exp_f32_e32 v247, v247
	v_exp_f32_e32 v248, v248
	v_exp_f32_e32 v249, v249
	v_exp_f32_e32 v250, v250
	v_exp_f32_e32 v251, v251
	v_cvt_pk_bf16_f32 v160, v236, v237
	v_cvt_pk_bf16_f32 v161, v238, v239
	v_cvt_pk_bf16_f32 v162, v240, v241
	v_cvt_pk_bf16_f32 v163, v242, v243
	v_cvt_pk_bf16_f32 v164, v244, v245
	v_cvt_pk_bf16_f32 v165, v246, v247
	v_cvt_pk_bf16_f32 v166, v248, v249
	v_cvt_pk_bf16_f32 v167, v250, v251

.Ldg_nb1_6:
	v_max3_f32 v64, v236, v237, v238
	v_max3_f32 v64, v64, v239, v240
	v_max3_f32 v64, v64, v241, v242
	v_max3_f32 v64, v64, v243, v244
	v_max3_f32 v64, v64, v245, v246
	v_max3_f32 v64, v64, v247, v248
	v_max3_f32 v64, v64, v249, v250
	v_max_f32_e32 v64, v64, v251
	v_cmp_lt_f32_e32 vcc, s97, v64
	s_cbranch_vccnz .Ldg_rare1_6
	s_waitcnt lgkmcnt(3)
	v_mfma_f32_32x32x16_bf16 v[32:47], v[200:203], v[130:133], v[32:47]
	ds_read_b128 v[126:129], v195 offset:49152
	ds_read_b128 v[114:117], v195 offset:53248
	v_exp_f32_e32 v236, v236
	v_exp_f32_e32 v237, v237
	v_exp_f32_e32 v238, v238
	s_waitcnt lgkmcnt(4)
	v_mfma_f32_32x32x16_bf16 v[48:63], v[200:203], v[134:137], v[48:63]
	ds_read_b128 v[122:125], v196 offset:49152
	ds_read_b128 v[118:121], v196 offset:53248
	v_exp_f32_e32 v239, v239
	v_exp_f32_e32 v240, v240
	v_exp_f32_e32 v241, v241
	s_waitcnt lgkmcnt(5)
	v_mfma_f32_32x32x16_bf16 v[32:47], v[204:207], v[138:141], v[32:47]
	v_exp_f32_e32 v242, v242
	v_exp_f32_e32 v243, v243
	v_exp_f32_e32 v244, v244
	s_waitcnt lgkmcnt(4)
	v_mfma_f32_32x32x16_bf16 v[48:63], v[204:207], v[142:145], v[48:63]
	v_exp_f32_e32 v245, v245
	v_exp_f32_e32 v246, v246
	v_exp_f32_e32 v247, v247
	v_exp_f32_e32 v248, v248
	v_exp_f32_e32 v249, v249
	v_exp_f32_e32 v250, v250
	v_exp_f32_e32 v251, v251
	v_cvt_pk_bf16_f32 v160, v236, v237
	v_cvt_pk_bf16_f32 v161, v238, v239
	v_cvt_pk_bf16_f32 v162, v240, v241
	v_cvt_pk_bf16_f32 v163, v242, v243
	v_cvt_pk_bf16_f32 v164, v244, v245
	v_cvt_pk_bf16_f32 v165, v246, v247
	v_cvt_pk_bf16_f32 v166, v248, v249
	v_cvt_pk_bf16_f32 v167, v250, v251

.Ldg_nb1_11:
	v_max3_f32 v64, v236, v237, v238
	v_max3_f32 v64, v64, v239, v240
	v_max3_f32 v64, v64, v241, v242
	v_max3_f32 v64, v64, v243, v244
	v_max3_f32 v64, v64, v245, v246
	v_max3_f32 v64, v64, v247, v248
	v_max3_f32 v64, v64, v249, v250
	v_max_f32_e32 v64, v64, v251
	v_cmp_lt_f32_e32 vcc, s97, v64
	s_cbranch_vccnz .Ldg_rare1_11
	v_mfma_f32_32x32x16_bf16 v[32:47], v[200:203], v[130:133], v[32:47]
	ds_read_b128 v[126:129], v195 offset:16384
	ds_read_b128 v[114:117], v195 offset:20480
	v_exp_f32_e32 v236, v236
	v_exp_f32_e32 v237, v237
	v_exp_f32_e32 v238, v238
	v_mfma_f32_32x32x16_bf16 v[48:63], v[200:203], v[134:137], v[48:63]
	ds_read_b128 v[122:125], v196 offset:16384
	ds_read_b128 v[118:121], v196 offset:20480
	v_exp_f32_e32 v239, v239
	v_exp_f32_e32 v240, v240
	v_exp_f32_e32 v241, v241
	v_mfma_f32_32x32x16_bf16 v[32:47], v[204:207], v[138:141], v[32:47]
	v_exp_f32_e32 v242, v242
	v_exp_f32_e32 v243, v243
	v_exp_f32_e32 v244, v244
	v_mfma_f32_32x32x16_bf16 v[48:63], v[204:207], v[142:145], v[48:63]
	v_exp_f32_e32 v245, v245
	v_exp_f32_e32 v246, v246
	v_exp_f32_e32 v247, v247
	v_exp_f32_e32 v248, v248
	v_exp_f32_e32 v249, v249
	v_exp_f32_e32 v250, v250
	v_exp_f32_e32 v251, v251
	v_cvt_pk_bf16_f32 v160, v236, v237
	v_cvt_pk_bf16_f32 v161, v238, v239
	v_cvt_pk_bf16_f32 v162, v240, v241
	v_cvt_pk_bf16_f32 v163, v242, v243
	v_cvt_pk_bf16_f32 v164, v244, v245
	v_cvt_pk_bf16_f32 v165, v246, v247
	v_cvt_pk_bf16_f32 v166, v248, v249
	v_cvt_pk_bf16_f32 v167, v250, v251

.Ldg_nb1_14:
	v_max3_f32 v64, v236, v237, v238
	v_max3_f32 v64, v64, v239, v240
	v_max3_f32 v64, v64, v241, v242
	v_max3_f32 v64, v64, v243, v244
	v_max3_f32 v64, v64, v245, v246
	v_max3_f32 v64, v64, v247, v248
	v_max3_f32 v64, v64, v249, v250
	v_max_f32_e32 v64, v64, v251
	v_cmp_lt_f32_e32 vcc, s97, v64
	s_cbranch_vccnz .Ldg_rare1_14
	v_mfma_f32_32x32x16_bf16 v[32:47], v[200:203], v[130:133], v[32:47]
	ds_read_b128 v[126:129], v195 offset:49152
	ds_read_b128 v[114:117], v195 offset:53248
	v_exp_f32_e32 v236, v236
	v_exp_f32_e32 v237, v237
	v_exp_f32_e32 v238, v238
	v_mfma_f32_32x32x16_bf16 v[48:63], v[200:203], v[134:137], v[48:63]
	ds_read_b128 v[122:125], v196 offset:49152
	ds_read_b128 v[118:121], v196 offset:53248
	v_exp_f32_e32 v239, v239
	v_exp_f32_e32 v240, v240
	v_exp_f32_e32 v241, v241
	v_mfma_f32_32x32x16_bf16 v[32:47], v[204:207], v[138:141], v[32:47]
	v_exp_f32_e32 v242, v242
	v_exp_f32_e32 v243, v243
	v_exp_f32_e32 v244, v244
	v_mfma_f32_32x32x16_bf16 v[48:63], v[204:207], v[142:145], v[48:63]
	v_exp_f32_e32 v245, v245
	v_exp_f32_e32 v246, v246
	v_exp_f32_e32 v247, v247
	v_exp_f32_e32 v248, v248
	v_exp_f32_e32 v249, v249
	v_exp_f32_e32 v250, v250
	v_exp_f32_e32 v251, v251
	v_cvt_pk_bf16_f32 v160, v236, v237
	v_cvt_pk_bf16_f32 v161, v238, v239
	v_cvt_pk_bf16_f32 v162, v240, v241
	v_cvt_pk_bf16_f32 v163, v242, v243
	v_cvt_pk_bf16_f32 v164, v244, v245
	v_cvt_pk_bf16_f32 v165, v246, v247
	v_cvt_pk_bf16_f32 v166, v248, v249
	v_cvt_pk_bf16_f32 v167, v250, v251

.Ldg_rare0_2:
	s_nop 15
	v_mov_b32_e32 v65, v64
	s_nop 1
	v_permlane32_swap_b32_e32 v64, v65
	v_max_f32_e32 v64, v64, v65
	v_max_f32_e32 v65, v64, v64
	v_max_f32_e32 v65, 0, v65
	v_add_f32_e32 v149, v149, v65
	v_sub_f32_e32 v66, v66, v65
	v_sub_f32_e32 v67, v67, v65
	v_sub_f32_e32 v68, v68, v65
	v_sub_f32_e32 v69, v69, v65
	v_sub_f32_e32 v70, v70, v65
	v_sub_f32_e32 v71, v71, v65
	v_sub_f32_e32 v72, v72, v65
	v_sub_f32_e32 v73, v73, v65
	v_sub_f32_e32 v74, v74, v65
	v_sub_f32_e32 v75, v75, v65
	v_sub_f32_e32 v76, v76, v65
	v_sub_f32_e32 v77, v77, v65
	v_sub_f32_e32 v78, v78, v65
	v_sub_f32_e32 v79, v79, v65
	v_sub_f32_e32 v80, v80, v65
	v_sub_f32_e32 v81, v81, v65
	v_sub_f32_e32 v236, v236, v65
	v_sub_f32_e32 v237, v237, v65
	v_sub_f32_e32 v238, v238, v65
	v_sub_f32_e32 v239, v239, v65
	v_sub_f32_e32 v240, v240, v65
	v_sub_f32_e32 v241, v241, v65
	v_sub_f32_e32 v242, v242, v65
	v_sub_f32_e32 v243, v243, v65
	v_sub_f32_e32 v244, v244, v65
	v_sub_f32_e32 v245, v245, v65
	v_sub_f32_e32 v246, v246, v65
	v_sub_f32_e32 v247, v247, v65
	v_sub_f32_e32 v248, v248, v65
	v_sub_f32_e32 v249, v249, v65
	v_sub_f32_e32 v250, v250, v65
	v_sub_f32_e32 v251, v251, v65
	v_exp_f32_e64 v64, -v65
	s_nop 0
	ds_write_b32 v198, v64
	ds_read_b128 v[160:163], v197
	ds_read_b128 v[164:167], v197 offset:32
	ds_read_b128 v[168:171], v197 offset:64
	ds_read_b128 v[172:175], v197 offset:96
	v_mul_f32_e32 v184, v184, v64
	s_waitcnt lgkmcnt(0)
	v_pk_mul_f32 v[0:1], v[0:1], v[160:161]
	v_pk_mul_f32 v[2:3], v[2:3], v[162:163]
	v_pk_mul_f32 v[4:5], v[4:5], v[164:165]
	v_pk_mul_f32 v[6:7], v[6:7], v[166:167]
	v_pk_mul_f32 v[8:9], v[8:9], v[168:169]
	v_pk_mul_f32 v[10:11], v[10:11], v[170:171]
	v_pk_mul_f32 v[12:13], v[12:13], v[172:173]
	v_pk_mul_f32 v[14:15], v[14:15], v[174:175]
	v_pk_mul_f32 v[16:17], v[16:17], v[160:161]
	v_pk_mul_f32 v[18:19], v[18:19], v[162:163]
	v_pk_mul_f32 v[20:21], v[20:21], v[164:165]
	v_pk_mul_f32 v[22:23], v[22:23], v[166:167]
	v_pk_mul_f32 v[24:25], v[24:25], v[168:169]
	v_pk_mul_f32 v[26:27], v[26:27], v[170:171]
	v_pk_mul_f32 v[28:29], v[28:29], v[172:173]
	v_pk_mul_f32 v[30:31], v[30:31], v[174:175]
	v_pk_mul_f32 v[32:33], v[32:33], v[160:161]
	v_pk_mul_f32 v[34:35], v[34:35], v[162:163]
	v_pk_mul_f32 v[36:37], v[36:37], v[164:165]
	v_pk_mul_f32 v[38:39], v[38:39], v[166:167]
	v_pk_mul_f32 v[40:41], v[40:41], v[168:169]
	v_pk_mul_f32 v[42:43], v[42:43], v[170:171]
	v_pk_mul_f32 v[44:45], v[44:45], v[172:173]
	v_pk_mul_f32 v[46:47], v[46:47], v[174:175]
	v_pk_mul_f32 v[48:49], v[48:49], v[160:161]
	v_pk_mul_f32 v[50:51], v[50:51], v[162:163]
	v_pk_mul_f32 v[52:53], v[52:53], v[164:165]
	v_pk_mul_f32 v[54:55], v[54:55], v[166:167]
	v_pk_mul_f32 v[56:57], v[56:57], v[168:169]
	v_pk_mul_f32 v[58:59], v[58:59], v[170:171]
	v_pk_mul_f32 v[60:61], v[60:61], v[172:173]
	v_pk_mul_f32 v[62:63], v[62:63], v[174:175]
	v_sub_f32_e32 v64, v253, v149
	v_mov_b32_e32 v220, v64
	v_mov_b32_e32 v221, v64
	v_mov_b32_e32 v222, v64
	v_mov_b32_e32 v223, v64
	v_mov_b32_e32 v224, v64
	v_mov_b32_e32 v225, v64
	v_mov_b32_e32 v226, v64
	v_mov_b32_e32 v227, v64
	v_mov_b32_e32 v228, v64
	v_mov_b32_e32 v229, v64
	v_mov_b32_e32 v230, v64
	v_mov_b32_e32 v231, v64
	v_mov_b32_e32 v232, v64
	v_mov_b32_e32 v233, v64
	v_mov_b32_e32 v234, v64
	v_mov_b32_e32 v235, v64
	s_branch .Ldg_back0_2
.Ldg_rare1_3:
	s_waitcnt lgkmcnt(0)
	v_mfma_f32_32x32x16_bf16 v[32:47], v[200:203], v[130:133], v[32:47]
	v_mfma_f32_32x32x16_bf16 v[48:63], v[200:203], v[134:137], v[48:63]
	v_mfma_f32_32x32x16_bf16 v[32:47], v[204:207], v[138:141], v[32:47]
	v_mfma_f32_32x32x16_bf16 v[48:63], v[204:207], v[142:145], v[48:63]
	s_nop 15
	v_mov_b32_e32 v65, v64
	s_nop 1
	v_permlane32_swap_b32_e32 v64, v65
	v_max_f32_e32 v64, v64, v65
	v_max_f32_e32 v65, v64, v64
	v_max_f32_e32 v65, 0, v65
	v_add_f32_e32 v149, v149, v65
	v_sub_f32_e32 v236, v236, v65
	v_sub_f32_e32 v237, v237, v65
	v_sub_f32_e32 v238, v238, v65
	v_sub_f32_e32 v239, v239, v65
	v_sub_f32_e32 v240, v240, v65
	v_sub_f32_e32 v241, v241, v65
	v_sub_f32_e32 v242, v242, v65
	v_sub_f32_e32 v243, v243, v65
	v_sub_f32_e32 v244, v244, v65
	v_sub_f32_e32 v245, v245, v65
	v_sub_f32_e32 v246, v246, v65
	v_sub_f32_e32 v247, v247, v65
	v_sub_f32_e32 v248, v248, v65
	v_sub_f32_e32 v249, v249, v65
	v_sub_f32_e32 v250, v250, v65
	v_sub_f32_e32 v251, v251, v65
	v_exp_f32_e64 v64, -v65
	s_nop 0
	ds_write_b32 v198, v64
	ds_read_b128 v[160:163], v197
	ds_read_b128 v[164:167], v197 offset:32
	ds_read_b128 v[168:171], v197 offset:64
	ds_read_b128 v[172:175], v197 offset:96
	v_mul_f32_e32 v184, v184, v64
	s_waitcnt lgkmcnt(0)
	v_pk_mul_f32 v[0:1], v[0:1], v[160:161]
	v_pk_mul_f32 v[2:3], v[2:3], v[162:163]
	v_pk_mul_f32 v[4:5], v[4:5], v[164:165]
	v_pk_mul_f32 v[6:7], v[6:7], v[166:167]
	v_pk_mul_f32 v[8:9], v[8:9], v[168:169]
	v_pk_mul_f32 v[10:11], v[10:11], v[170:171]
	v_pk_mul_f32 v[12:13], v[12:13], v[172:173]
	v_pk_mul_f32 v[14:15], v[14:15], v[174:175]
	v_pk_mul_f32 v[16:17], v[16:17], v[160:161]
	v_pk_mul_f32 v[18:19], v[18:19], v[162:163]
	v_pk_mul_f32 v[20:21], v[20:21], v[164:165]
	v_pk_mul_f32 v[22:23], v[22:23], v[166:167]
	v_pk_mul_f32 v[24:25], v[24:25], v[168:169]
	v_pk_mul_f32 v[26:27], v[26:27], v[170:171]
	v_pk_mul_f32 v[28:29], v[28:29], v[172:173]
	v_pk_mul_f32 v[30:31], v[30:31], v[174:175]
	v_pk_mul_f32 v[32:33], v[32:33], v[160:161]
	v_pk_mul_f32 v[34:35], v[34:35], v[162:163]
	v_pk_mul_f32 v[36:37], v[36:37], v[164:165]
	v_pk_mul_f32 v[38:39], v[38:39], v[166:167]
	v_pk_mul_f32 v[40:41], v[40:41], v[168:169]
	v_pk_mul_f32 v[42:43], v[42:43], v[170:171]
	v_pk_mul_f32 v[44:45], v[44:45], v[172:173]
	v_pk_mul_f32 v[46:47], v[46:47], v[174:175]
	v_pk_mul_f32 v[48:49], v[48:49], v[160:161]
	v_pk_mul_f32 v[50:51], v[50:51], v[162:163]
	v_pk_mul_f32 v[52:53], v[52:53], v[164:165]
	v_pk_mul_f32 v[54:55], v[54:55], v[166:167]
	v_pk_mul_f32 v[56:57], v[56:57], v[168:169]
	v_pk_mul_f32 v[58:59], v[58:59], v[170:171]
	v_pk_mul_f32 v[60:61], v[60:61], v[172:173]
	v_pk_mul_f32 v[62:63], v[62:63], v[174:175]
	ds_read_b128 v[126:129], v195 offset:16384
	ds_read_b128 v[114:117], v195 offset:20480
	ds_read_b128 v[122:125], v196 offset:16384
	ds_read_b128 v[118:121], v196 offset:20480
	v_exp_f32_e32 v236, v236
	v_exp_f32_e32 v237, v237
	v_exp_f32_e32 v238, v238
	v_exp_f32_e32 v239, v239
	v_exp_f32_e32 v240, v240
	v_exp_f32_e32 v241, v241
	v_exp_f32_e32 v242, v242
	v_exp_f32_e32 v243, v243
	v_exp_f32_e32 v244, v244
	v_exp_f32_e32 v245, v245
	v_exp_f32_e32 v246, v246
	v_exp_f32_e32 v247, v247
	v_exp_f32_e32 v248, v248
	v_exp_f32_e32 v249, v249
	v_exp_f32_e32 v250, v250
	v_exp_f32_e32 v251, v251
	v_cvt_pk_bf16_f32 v160, v236, v237
	v_cvt_pk_bf16_f32 v161, v238, v239
	v_cvt_pk_bf16_f32 v162, v240, v241
	v_cvt_pk_bf16_f32 v163, v242, v243
	v_cvt_pk_bf16_f32 v164, v244, v245
	v_cvt_pk_bf16_f32 v165, v246, v247
	v_cvt_pk_bf16_f32 v166, v248, v249
	v_cvt_pk_bf16_f32 v167, v250, v251
	s_branch .Ldg_join1_3

.Ldg_rare1_6:
	s_waitcnt lgkmcnt(0)
	v_mfma_f32_32x32x16_bf16 v[32:47], v[200:203], v[130:133], v[32:47]
	v_mfma_f32_32x32x16_bf16 v[48:63], v[200:203], v[134:137], v[48:63]
	v_mfma_f32_32x32x16_bf16 v[32:47], v[204:207], v[138:141], v[32:47]
	v_mfma_f32_32x32x16_bf16 v[48:63], v[204:207], v[142:145], v[48:63]
	s_nop 15
	v_mov_b32_e32 v65, v64
	s_nop 1
	v_permlane32_swap_b32_e32 v64, v65
	v_max_f32_e32 v64, v64, v65
	v_max_f32_e32 v65, v64, v64
	v_max_f32_e32 v65, 0, v65
	v_add_f32_e32 v149, v149, v65
	v_sub_f32_e32 v236, v236, v65
	v_sub_f32_e32 v237, v237, v65
	v_sub_f32_e32 v238, v238, v65
	v_sub_f32_e32 v239, v239, v65
	v_sub_f32_e32 v240, v240, v65
	v_sub_f32_e32 v241, v241, v65
	v_sub_f32_e32 v242, v242, v65
	v_sub_f32_e32 v243, v243, v65
	v_sub_f32_e32 v244, v244, v65
	v_sub_f32_e32 v245, v245, v65
	v_sub_f32_e32 v246, v246, v65
	v_sub_f32_e32 v247, v247, v65
	v_sub_f32_e32 v248, v248, v65
	v_sub_f32_e32 v249, v249, v65
	v_sub_f32_e32 v250, v250, v65
	v_sub_f32_e32 v251, v251, v65
	v_exp_f32_e64 v64, -v65
	s_nop 0
	ds_write_b32 v198, v64
	ds_read_b128 v[160:163], v197
	ds_read_b128 v[164:167], v197 offset:32
	ds_read_b128 v[168:171], v197 offset:64
	ds_read_b128 v[172:175], v197 offset:96
	v_mul_f32_e32 v184, v184, v64
	s_waitcnt lgkmcnt(0)
	v_pk_mul_f32 v[0:1], v[0:1], v[160:161]
	v_pk_mul_f32 v[2:3], v[2:3], v[162:163]
	v_pk_mul_f32 v[4:5], v[4:5], v[164:165]
	v_pk_mul_f32 v[6:7], v[6:7], v[166:167]
	v_pk_mul_f32 v[8:9], v[8:9], v[168:169]
	v_pk_mul_f32 v[10:11], v[10:11], v[170:171]
	v_pk_mul_f32 v[12:13], v[12:13], v[172:173]
	v_pk_mul_f32 v[14:15], v[14:15], v[174:175]
	v_pk_mul_f32 v[16:17], v[16:17], v[160:161]
	v_pk_mul_f32 v[18:19], v[18:19], v[162:163]
	v_pk_mul_f32 v[20:21], v[20:21], v[164:165]
	v_pk_mul_f32 v[22:23], v[22:23], v[166:167]
	v_pk_mul_f32 v[24:25], v[24:25], v[168:169]
	v_pk_mul_f32 v[26:27], v[26:27], v[170:171]
	v_pk_mul_f32 v[28:29], v[28:29], v[172:173]
	v_pk_mul_f32 v[30:31], v[30:31], v[174:175]
	v_pk_mul_f32 v[32:33], v[32:33], v[160:161]
	v_pk_mul_f32 v[34:35], v[34:35], v[162:163]
	v_pk_mul_f32 v[36:37], v[36:37], v[164:165]
	v_pk_mul_f32 v[38:39], v[38:39], v[166:167]
	v_pk_mul_f32 v[40:41], v[40:41], v[168:169]
	v_pk_mul_f32 v[42:43], v[42:43], v[170:171]
	v_pk_mul_f32 v[44:45], v[44:45], v[172:173]
	v_pk_mul_f32 v[46:47], v[46:47], v[174:175]
	v_pk_mul_f32 v[48:49], v[48:49], v[160:161]
	v_pk_mul_f32 v[50:51], v[50:51], v[162:163]
	v_pk_mul_f32 v[52:53], v[52:53], v[164:165]
	v_pk_mul_f32 v[54:55], v[54:55], v[166:167]
	v_pk_mul_f32 v[56:57], v[56:57], v[168:169]
	v_pk_mul_f32 v[58:59], v[58:59], v[170:171]
	v_pk_mul_f32 v[60:61], v[60:61], v[172:173]
	v_pk_mul_f32 v[62:63], v[62:63], v[174:175]
	ds_read_b128 v[126:129], v195 offset:49152
	ds_read_b128 v[114:117], v195 offset:53248
	ds_read_b128 v[122:125], v196 offset:49152
	ds_read_b128 v[118:121], v196 offset:53248
	v_exp_f32_e32 v236, v236
	v_exp_f32_e32 v237, v237
	v_exp_f32_e32 v238, v238
	v_exp_f32_e32 v239, v239
	v_exp_f32_e32 v240, v240
	v_exp_f32_e32 v241, v241
	v_exp_f32_e32 v242, v242
	v_exp_f32_e32 v243, v243
	v_exp_f32_e32 v244, v244
	v_exp_f32_e32 v245, v245
	v_exp_f32_e32 v246, v246
	v_exp_f32_e32 v247, v247
	v_exp_f32_e32 v248, v248
	v_exp_f32_e32 v249, v249
	v_exp_f32_e32 v250, v250
	v_exp_f32_e32 v251, v251
	v_cvt_pk_bf16_f32 v160, v236, v237
	v_cvt_pk_bf16_f32 v161, v238, v239
	v_cvt_pk_bf16_f32 v162, v240, v241
	v_cvt_pk_bf16_f32 v163, v242, v243
	v_cvt_pk_bf16_f32 v164, v244, v245
	v_cvt_pk_bf16_f32 v165, v246, v247
	v_cvt_pk_bf16_f32 v166, v248, v249
	v_cvt_pk_bf16_f32 v167, v250, v251
	s_branch .Ldg_join1_6

.Lgq_nold1:
	ds_read_b128 v[232:235], v227 offset:8192
	ds_read_b128 v[236:239], v227 offset:12288
	ds_read_b128 v[240:243], v228 offset:8192
	ds_read_b128 v[244:247], v228 offset:12288
	v_max3_f32 v252, v80, v81, v82
	v_max3_f32 v252, v252, v83, v84
	v_max3_f32 v252, v252, v85, v86
	v_max3_f32 v252, v252, v87, v88
	v_max3_f32 v252, v252, v89, v90
	v_max3_f32 v252, v252, v91, v92
	v_max3_f32 v252, v252, v93, v94
	v_max_f32_e32 v252, v252, v95
	v_max3_f32 v253, v64, v65, v66
	v_max3_f32 v253, v253, v67, v68
	v_max3_f32 v253, v253, v69, v70
	v_max3_f32 v253, v253, v71, v72
	v_max3_f32 v253, v253, v73, v74
	v_max3_f32 v253, v253, v75, v76
	v_max3_f32 v253, v253, v77, v78
	v_max_f32_e32 v253, v253, v79
	v_mov_b32_e32 v248, v252
	s_nop 1
	v_permlane32_swap_b32_e32 v252, v248
	v_max_f32_e32 v252, v252, v248
	v_mov_b32_e32 v231, v252
	v_sub_f32_e32 v80, v80, v252
	v_sub_f32_e32 v81, v81, v252
	v_sub_f32_e32 v82, v82, v252
	v_sub_f32_e32 v83, v83, v252
	v_sub_f32_e32 v84, v84, v252
	v_sub_f32_e32 v85, v85, v252
	v_sub_f32_e32 v86, v86, v252
	v_sub_f32_e32 v87, v87, v252
	v_sub_f32_e32 v88, v88, v252
	v_sub_f32_e32 v89, v89, v252
	v_sub_f32_e32 v90, v90, v252
	v_sub_f32_e32 v91, v91, v252
	v_sub_f32_e32 v92, v92, v252
	v_sub_f32_e32 v93, v93, v252
	v_sub_f32_e32 v94, v94, v252
	v_sub_f32_e32 v95, v95, v252
	v_xor_b32_e32 v152, 0x80000000, v231
	v_mov_b32_e32 v153, v152
	v_mov_b32_e32 v154, v152
	v_mov_b32_e32 v155, v152
	v_mov_b32_e32 v156, v152
	v_mov_b32_e32 v157, v152
	v_mov_b32_e32 v158, v152
	v_mov_b32_e32 v159, v152
	v_mov_b32_e32 v160, v152
	v_mov_b32_e32 v161, v152
	v_mov_b32_e32 v162, v152
	v_mov_b32_e32 v163, v152
	v_mov_b32_e32 v164, v152
	v_mov_b32_e32 v165, v152
	v_mov_b32_e32 v166, v152
	v_mov_b32_e32 v167, v152
	v_mov_b32_e32 v248, v253
	s_nop 1
	v_permlane32_swap_b32_e32 v253, v248
	v_max_f32_e32 v253, v253, v248
	v_mov_b32_e32 v223, v253
	v_sub_f32_e32 v64, v64, v253
	v_sub_f32_e32 v65, v65, v253
	v_sub_f32_e32 v66, v66, v253
	v_sub_f32_e32 v67, v67, v253
	v_sub_f32_e32 v68, v68, v253
	v_sub_f32_e32 v69, v69, v253
	v_sub_f32_e32 v70, v70, v253
	v_sub_f32_e32 v71, v71, v253
	v_sub_f32_e32 v72, v72, v253
	v_sub_f32_e32 v73, v73, v253
	v_sub_f32_e32 v74, v74, v253
	v_sub_f32_e32 v75, v75, v253
	v_sub_f32_e32 v76, v76, v253
	v_sub_f32_e32 v77, v77, v253
	v_sub_f32_e32 v78, v78, v253
	v_sub_f32_e32 v79, v79, v253
	v_xor_b32_e32 v168, 0x80000000, v223
	v_mov_b32_e32 v169, v168
	v_mov_b32_e32 v170, v168
	v_mov_b32_e32 v171, v168
	v_mov_b32_e32 v172, v168
	v_mov_b32_e32 v173, v168
	v_mov_b32_e32 v174, v168
	v_mov_b32_e32 v175, v168
	v_mov_b32_e32 v176, v168
	v_mov_b32_e32 v177, v168
	v_mov_b32_e32 v178, v168
	v_mov_b32_e32 v179, v168
	v_mov_b32_e32 v180, v168
	v_mov_b32_e32 v181, v168
	v_mov_b32_e32 v182, v168
	v_mov_b32_e32 v183, v168
	v_exp_f32_e32 v80, v80
	v_exp_f32_e32 v81, v81
	v_exp_f32_e32 v82, v82
	v_exp_f32_e32 v83, v83
	v_exp_f32_e32 v84, v84
	v_exp_f32_e32 v85, v85
	v_exp_f32_e32 v86, v86
	v_exp_f32_e32 v87, v87
	v_exp_f32_e32 v88, v88
	v_exp_f32_e32 v89, v89
	v_exp_f32_e32 v90, v90
	v_exp_f32_e32 v91, v91
	v_exp_f32_e32 v92, v92
	v_exp_f32_e32 v93, v93
	v_exp_f32_e32 v94, v94
	v_exp_f32_e32 v95, v95
	v_add_f32_e32 v104, v80, v81
	v_add_f32_e32 v105, v82, v83
	v_add_f32_e32 v106, v84, v85
	v_add_f32_e32 v107, v86, v87
	v_add_f32_e32 v108, v88, v89
	v_add_f32_e32 v109, v90, v91
	v_add_f32_e32 v110, v92, v93
	v_add_f32_e32 v111, v94, v95
	v_add_f32_e32 v104, v104, v105
	v_add_f32_e32 v106, v106, v107
	v_add_f32_e32 v108, v108, v109
	v_add_f32_e32 v110, v110, v111
	v_add_f32_e32 v104, v104, v106
	v_add_f32_e32 v108, v108, v110
	v_add_f32_e32 v104, v104, v108
	v_add_f32_e32 v250, v250, v104
	v_cvt_pk_bf16_f32 v96, v80, v81
	v_cvt_pk_bf16_f32 v97, v82, v83
	v_cvt_pk_bf16_f32 v98, v84, v85
	v_cvt_pk_bf16_f32 v99, v86, v87
	v_cvt_pk_bf16_f32 v100, v88, v89
	v_cvt_pk_bf16_f32 v101, v90, v91
	v_cvt_pk_bf16_f32 v102, v92, v93
	v_cvt_pk_bf16_f32 v103, v94, v95
	v_exp_f32_e32 v64, v64
	v_exp_f32_e32 v65, v65
	v_exp_f32_e32 v66, v66
	v_exp_f32_e32 v67, v67
	v_exp_f32_e32 v68, v68
	v_exp_f32_e32 v69, v69
	v_exp_f32_e32 v70, v70
	v_exp_f32_e32 v71, v71
	v_exp_f32_e32 v72, v72
	v_exp_f32_e32 v73, v73
	v_exp_f32_e32 v74, v74
	v_exp_f32_e32 v75, v75
	v_exp_f32_e32 v76, v76
	v_exp_f32_e32 v77, v77
	v_exp_f32_e32 v78, v78
	v_exp_f32_e32 v79, v79
	v_add_f32_e32 v104, v64, v65
	v_add_f32_e32 v105, v66, v67
	v_add_f32_e32 v106, v68, v69
	v_add_f32_e32 v107, v70, v71
	v_add_f32_e32 v108, v72, v73
	v_add_f32_e32 v109, v74, v75
	v_add_f32_e32 v110, v76, v77
	v_add_f32_e32 v111, v78, v79
	v_add_f32_e32 v104, v104, v105
	v_add_f32_e32 v106, v106, v107
	v_add_f32_e32 v108, v108, v109
	v_add_f32_e32 v110, v110, v111
	v_add_f32_e32 v104, v104, v106
	v_add_f32_e32 v108, v108, v110
	v_add_f32_e32 v104, v104, v108
	v_add_f32_e32 v251, v251, v104
	v_cvt_pk_bf16_f32 v104, v64, v65
	v_cvt_pk_bf16_f32 v105, v66, v67
	v_cvt_pk_bf16_f32 v106, v68, v69
	v_cvt_pk_bf16_f32 v107, v70, v71
	v_cvt_pk_bf16_f32 v108, v72, v73
	v_cvt_pk_bf16_f32 v109, v74, v75
	v_cvt_pk_bf16_f32 v110, v76, v77
	v_cvt_pk_bf16_f32 v111, v78, v79
	s_waitcnt lgkmcnt(7)
	v_mfma_f32_32x32x16_bf16 v[80:95], v[198:201], v[112:115], v[152:167]
	s_waitcnt lgkmcnt(6)
	v_mfma_f32_32x32x16_bf16 v[80:95], v[202:205], v[116:119], v[80:95]
	s_waitcnt lgkmcnt(5)
	v_mfma_f32_32x32x16_bf16 v[80:95], v[206:209], v[124:127], v[80:95]
	s_waitcnt lgkmcnt(4)
	v_mfma_f32_32x32x16_bf16 v[80:95], v[210:213], v[128:131], v[80:95]
	v_mfma_f32_32x32x16_bf16 v[64:79], v[198:201], v[132:135], v[168:183]
	v_mfma_f32_32x32x16_bf16 v[64:79], v[202:205], v[136:139], v[64:79]
	v_mfma_f32_32x32x16_bf16 v[64:79], v[206:209], v[140:143], v[64:79]
	v_mfma_f32_32x32x16_bf16 v[64:79], v[210:213], v[144:147], v[64:79]
	s_waitcnt lgkmcnt(3)
	v_mfma_f32_32x32x16_bf16 v[48:63], v[96:99], v[232:235], v[48:63]
	s_waitcnt lgkmcnt(2)
	v_mfma_f32_32x32x16_bf16 v[32:47], v[96:99], v[236:239], v[32:47]
	v_mfma_f32_32x32x16_bf16 v[16:31], v[104:107], v[232:235], v[16:31]
	v_mfma_f32_32x32x16_bf16 v[0:15], v[104:107], v[236:239], v[0:15]
	s_nop 1
	v_max3_f32 v252, v80, v81, v82
	v_max3_f32 v252, v252, v83, v84
	v_max3_f32 v252, v252, v85, v86
	v_max3_f32 v252, v252, v87, v88
	v_max3_f32 v252, v252, v89, v90
	v_max3_f32 v252, v252, v91, v92
	v_max3_f32 v252, v252, v93, v94
	v_max_f32_e32 v252, v252, v95
	s_waitcnt lgkmcnt(1)
	v_mfma_f32_32x32x16_bf16 v[48:63], v[100:103], v[240:243], v[48:63]
	s_waitcnt lgkmcnt(0)
	v_mfma_f32_32x32x16_bf16 v[32:47], v[100:103], v[244:247], v[32:47]
	v_mfma_f32_32x32x16_bf16 v[16:31], v[108:111], v[240:243], v[16:31]
	v_mfma_f32_32x32x16_bf16 v[0:15], v[108:111], v[244:247], v[0:15]
	ds_read_b128 v[232:235], v229 offset:8192
	ds_read_b128 v[236:239], v229 offset:12288
	ds_read_b128 v[240:243], v230 offset:8192
	ds_read_b128 v[244:247], v230 offset:12288
	v_max3_f32 v253, v64, v65, v66
	v_max3_f32 v253, v253, v67, v68
	v_max3_f32 v253, v253, v69, v70
	v_max3_f32 v253, v253, v71, v72
	v_max3_f32 v253, v253, v73, v74
	v_max3_f32 v253, v253, v75, v76
	v_max3_f32 v253, v253, v77, v78
	v_max_f32_e32 v253, v253, v79
	v_cmp_lt_f32_e32 vcc, s97, v252
	s_cbranch_vccnz .Lgq_rare3

.Lgq_nold6:
	ds_read_b128 v[232:235], v227 offset:24576
	ds_read_b128 v[236:239], v227 offset:28672
	ds_read_b128 v[240:243], v228 offset:24576
	ds_read_b128 v[244:247], v228 offset:28672
	v_max3_f32 v252, v80, v81, v82
	v_max3_f32 v252, v252, v83, v84
	v_max3_f32 v252, v252, v85, v86
	v_max3_f32 v252, v252, v87, v88
	v_max3_f32 v252, v252, v89, v90
	v_max3_f32 v252, v252, v91, v92
	v_max3_f32 v252, v252, v93, v94
	v_max_f32_e32 v252, v252, v95
	v_max3_f32 v253, v64, v65, v66
	v_max3_f32 v253, v253, v67, v68
	v_max3_f32 v253, v253, v69, v70
	v_max3_f32 v253, v253, v71, v72
	v_max3_f32 v253, v253, v73, v74
	v_max3_f32 v253, v253, v75, v76
	v_max3_f32 v253, v253, v77, v78
	v_max_f32_e32 v253, v253, v79
	v_cmp_lt_f32_e32 vcc, s97, v252
	s_cbranch_vccnz .Lgq_rare8

.Lgq_back9:
	v_exp_f32_e32 v80, v80
	v_exp_f32_e32 v81, v81
	v_exp_f32_e32 v82, v82
	v_exp_f32_e32 v83, v83
	v_exp_f32_e32 v84, v84
	v_exp_f32_e32 v85, v85
	v_exp_f32_e32 v86, v86
	v_exp_f32_e32 v87, v87
	v_exp_f32_e32 v88, v88
	v_exp_f32_e32 v89, v89
	v_exp_f32_e32 v90, v90
	v_exp_f32_e32 v91, v91
	v_exp_f32_e32 v92, v92
	v_exp_f32_e32 v93, v93
	v_exp_f32_e32 v94, v94
	v_exp_f32_e32 v95, v95
	v_add_f32_e32 v104, v80, v81
	v_add_f32_e32 v105, v82, v83
	v_add_f32_e32 v106, v84, v85
	v_add_f32_e32 v107, v86, v87
	v_add_f32_e32 v108, v88, v89
	v_add_f32_e32 v109, v90, v91
	v_add_f32_e32 v110, v92, v93
	v_add_f32_e32 v111, v94, v95
	v_add_f32_e32 v104, v104, v105
	v_add_f32_e32 v106, v106, v107
	v_add_f32_e32 v108, v108, v109
	v_add_f32_e32 v110, v110, v111
	v_add_f32_e32 v104, v104, v106
	v_add_f32_e32 v108, v108, v110
	v_add_f32_e32 v104, v104, v108
	v_add_f32_e32 v250, v250, v104
	v_cvt_pk_bf16_f32 v96, v80, v81
	v_cvt_pk_bf16_f32 v97, v82, v83
	v_cvt_pk_bf16_f32 v98, v84, v85
	v_cvt_pk_bf16_f32 v99, v86, v87
	v_cvt_pk_bf16_f32 v100, v88, v89
	v_cvt_pk_bf16_f32 v101, v90, v91
	v_cvt_pk_bf16_f32 v102, v92, v93
	v_cvt_pk_bf16_f32 v103, v94, v95
	v_exp_f32_e32 v64, v64
	v_exp_f32_e32 v65, v65
	v_exp_f32_e32 v66, v66
	v_exp_f32_e32 v67, v67
	v_exp_f32_e32 v68, v68
	v_exp_f32_e32 v69, v69
	v_exp_f32_e32 v70, v70
	v_exp_f32_e32 v71, v71
	v_exp_f32_e32 v72, v72
	v_exp_f32_e32 v73, v73
	v_exp_f32_e32 v74, v74
	v_exp_f32_e32 v75, v75
	v_exp_f32_e32 v76, v76
	v_exp_f32_e32 v77, v77
	v_exp_f32_e32 v78, v78
	v_exp_f32_e32 v79, v79
	v_add_f32_e32 v104, v64, v65
	v_add_f32_e32 v105, v66, v67
	v_add_f32_e32 v106, v68, v69
	v_add_f32_e32 v107, v70, v71
	v_add_f32_e32 v108, v72, v73
	v_add_f32_e32 v109, v74, v75
	v_add_f32_e32 v110, v76, v77
	v_add_f32_e32 v111, v78, v79
	v_add_f32_e32 v104, v104, v105
	v_add_f32_e32 v106, v106, v107
	v_add_f32_e32 v108, v108, v109
	v_add_f32_e32 v110, v110, v111
	v_add_f32_e32 v104, v104, v106
	v_add_f32_e32 v108, v108, v110
	v_add_f32_e32 v104, v104, v108
	v_add_f32_e32 v251, v251, v104
	v_cvt_pk_bf16_f32 v104, v64, v65
	v_cvt_pk_bf16_f32 v105, v66, v67
	v_cvt_pk_bf16_f32 v106, v68, v69
	v_cvt_pk_bf16_f32 v107, v70, v71
	v_cvt_pk_bf16_f32 v108, v72, v73
	v_cvt_pk_bf16_f32 v109, v74, v75
	v_cvt_pk_bf16_f32 v110, v76, v77
	v_cvt_pk_bf16_f32 v111, v78, v79
	s_waitcnt lgkmcnt(7)
	v_mfma_f32_32x32x16_bf16 v[80:95], v[198:201], v[112:115], v[152:167]
	s_waitcnt lgkmcnt(6)
	v_mfma_f32_32x32x16_bf16 v[80:95], v[202:205], v[116:119], v[80:95]
	s_waitcnt lgkmcnt(5)
	v_mfma_f32_32x32x16_bf16 v[80:95], v[206:209], v[124:127], v[80:95]
	s_waitcnt lgkmcnt(4)
	v_mfma_f32_32x32x16_bf16 v[80:95], v[210:213], v[128:131], v[80:95]
	v_mfma_f32_32x32x16_bf16 v[64:79], v[198:201], v[132:135], v[168:183]
	v_mfma_f32_32x32x16_bf16 v[64:79], v[202:205], v[136:139], v[64:79]
	v_mfma_f32_32x32x16_bf16 v[64:79], v[206:209], v[140:143], v[64:79]
	v_mfma_f32_32x32x16_bf16 v[64:79], v[210:213], v[144:147], v[64:79]
	s_waitcnt lgkmcnt(3)
	v_mfma_f32_32x32x16_bf16 v[48:63], v[96:99], v[232:235], v[48:63]
	s_waitcnt lgkmcnt(2)
	v_mfma_f32_32x32x16_bf16 v[32:47], v[96:99], v[236:239], v[32:47]
	v_mfma_f32_32x32x16_bf16 v[16:31], v[104:107], v[232:235], v[16:31]
	v_mfma_f32_32x32x16_bf16 v[0:15], v[104:107], v[236:239], v[0:15]
	s_nop 1
	v_max3_f32 v252, v80, v81, v82
	v_max3_f32 v252, v252, v83, v84
	v_max3_f32 v252, v252, v85, v86
	v_max3_f32 v252, v252, v87, v88
	v_max3_f32 v252, v252, v89, v90
	v_max3_f32 v252, v252, v91, v92
	v_max3_f32 v252, v252, v93, v94
	v_max_f32_e32 v252, v252, v95
	s_waitcnt lgkmcnt(1)
	v_mfma_f32_32x32x16_bf16 v[48:63], v[100:103], v[240:243], v[48:63]
	s_waitcnt lgkmcnt(0)
	v_mfma_f32_32x32x16_bf16 v[32:47], v[100:103], v[244:247], v[32:47]
	v_mfma_f32_32x32x16_bf16 v[16:31], v[108:111], v[240:243], v[16:31]
	v_mfma_f32_32x32x16_bf16 v[0:15], v[108:111], v[244:247], v[0:15]
	ds_read_b128 v[232:235], v229 offset:24576
	ds_read_b128 v[236:239], v229 offset:28672
	ds_read_b128 v[240:243], v230 offset:24576
	ds_read_b128 v[244:247], v230 offset:28672
	v_max3_f32 v253, v64, v65, v66
	v_max3_f32 v253, v253, v67, v68
	v_max3_f32 v253, v253, v69, v70
	v_max3_f32 v253, v253, v71, v72
	v_max3_f32 v253, v253, v73, v74
	v_max3_f32 v253, v253, v75, v76
	v_max3_f32 v253, v253, v77, v78
	v_max_f32_e32 v253, v253, v79
	v_cmp_lt_f32_e32 vcc, s97, v252
	s_cbranch_vccnz .Lgq_rare12

.Lgq_nold15:
	ds_read_b128 v[232:235], v227 offset:8192
	ds_read_b128 v[236:239], v227 offset:12288
	ds_read_b128 v[240:243], v228 offset:8192
	ds_read_b128 v[244:247], v228 offset:12288
	v_max3_f32 v252, v80, v81, v82
	v_max3_f32 v252, v252, v83, v84
	v_max3_f32 v252, v252, v85, v86
	v_max3_f32 v252, v252, v87, v88
	v_max3_f32 v252, v252, v89, v90
	v_max3_f32 v252, v252, v91, v92
	v_max3_f32 v252, v252, v93, v94
	v_max_f32_e32 v252, v252, v95
	v_max3_f32 v253, v64, v65, v66
	v_max3_f32 v253, v253, v67, v68
	v_max3_f32 v253, v253, v69, v70
	v_max3_f32 v253, v253, v71, v72
	v_max3_f32 v253, v253, v73, v74
	v_max3_f32 v253, v253, v75, v76
	v_max3_f32 v253, v253, v77, v78
	v_max_f32_e32 v253, v253, v79
	v_cmp_lt_f32_e32 vcc, s97, v252
	s_cbranch_vccnz .Lgq_rare17

.Lgq_back18:
	v_exp_f32_e32 v80, v80
	v_exp_f32_e32 v81, v81
	v_exp_f32_e32 v82, v82
	v_exp_f32_e32 v83, v83
	v_exp_f32_e32 v84, v84
	v_exp_f32_e32 v85, v85
	v_exp_f32_e32 v86, v86
	v_exp_f32_e32 v87, v87
	v_exp_f32_e32 v88, v88
	v_exp_f32_e32 v89, v89
	v_exp_f32_e32 v90, v90
	v_exp_f32_e32 v91, v91
	v_exp_f32_e32 v92, v92
	v_exp_f32_e32 v93, v93
	v_exp_f32_e32 v94, v94
	v_exp_f32_e32 v95, v95
	v_add_f32_e32 v104, v80, v81
	v_add_f32_e32 v105, v82, v83
	v_add_f32_e32 v106, v84, v85
	v_add_f32_e32 v107, v86, v87
	v_add_f32_e32 v108, v88, v89
	v_add_f32_e32 v109, v90, v91
	v_add_f32_e32 v110, v92, v93
	v_add_f32_e32 v111, v94, v95
	v_add_f32_e32 v104, v104, v105
	v_add_f32_e32 v106, v106, v107
	v_add_f32_e32 v108, v108, v109
	v_add_f32_e32 v110, v110, v111
	v_add_f32_e32 v104, v104, v106
	v_add_f32_e32 v108, v108, v110
	v_add_f32_e32 v104, v104, v108
	v_add_f32_e32 v250, v250, v104
	v_cvt_pk_bf16_f32 v96, v80, v81
	v_cvt_pk_bf16_f32 v97, v82, v83
	v_cvt_pk_bf16_f32 v98, v84, v85
	v_cvt_pk_bf16_f32 v99, v86, v87
	v_cvt_pk_bf16_f32 v100, v88, v89
	v_cvt_pk_bf16_f32 v101, v90, v91
	v_cvt_pk_bf16_f32 v102, v92, v93
	v_cvt_pk_bf16_f32 v103, v94, v95
	v_exp_f32_e32 v64, v64
	v_exp_f32_e32 v65, v65
	v_exp_f32_e32 v66, v66
	v_exp_f32_e32 v67, v67
	v_exp_f32_e32 v68, v68
	v_exp_f32_e32 v69, v69
	v_exp_f32_e32 v70, v70
	v_exp_f32_e32 v71, v71
	v_exp_f32_e32 v72, v72
	v_exp_f32_e32 v73, v73
	v_exp_f32_e32 v74, v74
	v_exp_f32_e32 v75, v75
	v_exp_f32_e32 v76, v76
	v_exp_f32_e32 v77, v77
	v_exp_f32_e32 v78, v78
	v_exp_f32_e32 v79, v79
	v_add_f32_e32 v104, v64, v65
	v_add_f32_e32 v105, v66, v67
	v_add_f32_e32 v106, v68, v69
	v_add_f32_e32 v107, v70, v71
	v_add_f32_e32 v108, v72, v73
	v_add_f32_e32 v109, v74, v75
	v_add_f32_e32 v110, v76, v77
	v_add_f32_e32 v111, v78, v79
	v_add_f32_e32 v104, v104, v105
	v_add_f32_e32 v106, v106, v107
	v_add_f32_e32 v108, v108, v109
	v_add_f32_e32 v110, v110, v111
	v_add_f32_e32 v104, v104, v106
	v_add_f32_e32 v108, v108, v110
	v_add_f32_e32 v104, v104, v108
	v_add_f32_e32 v251, v251, v104
	v_cvt_pk_bf16_f32 v104, v64, v65
	v_cvt_pk_bf16_f32 v105, v66, v67
	v_cvt_pk_bf16_f32 v106, v68, v69
	v_cvt_pk_bf16_f32 v107, v70, v71
	v_cvt_pk_bf16_f32 v108, v72, v73
	v_cvt_pk_bf16_f32 v109, v74, v75
	v_cvt_pk_bf16_f32 v110, v76, v77
	v_cvt_pk_bf16_f32 v111, v78, v79
	s_waitcnt lgkmcnt(7)
	v_mfma_f32_32x32x16_bf16 v[80:95], v[198:201], v[112:115], v[152:167]
	s_waitcnt lgkmcnt(6)
	v_mfma_f32_32x32x16_bf16 v[80:95], v[202:205], v[116:119], v[80:95]
	s_waitcnt lgkmcnt(5)
	v_mfma_f32_32x32x16_bf16 v[80:95], v[206:209], v[124:127], v[80:95]
	s_waitcnt lgkmcnt(4)
	v_mfma_f32_32x32x16_bf16 v[80:95], v[210:213], v[128:131], v[80:95]
	v_mfma_f32_32x32x16_bf16 v[64:79], v[198:201], v[132:135], v[168:183]
	v_mfma_f32_32x32x16_bf16 v[64:79], v[202:205], v[136:139], v[64:79]
	v_mfma_f32_32x32x16_bf16 v[64:79], v[206:209], v[140:143], v[64:79]
	v_mfma_f32_32x32x16_bf16 v[64:79], v[210:213], v[144:147], v[64:79]
	s_waitcnt lgkmcnt(3)
	v_mfma_f32_32x32x16_bf16 v[48:63], v[96:99], v[232:235], v[48:63]
	s_waitcnt lgkmcnt(2)
	v_mfma_f32_32x32x16_bf16 v[32:47], v[96:99], v[236:239], v[32:47]
	v_mfma_f32_32x32x16_bf16 v[16:31], v[104:107], v[232:235], v[16:31]
	v_mfma_f32_32x32x16_bf16 v[0:15], v[104:107], v[236:239], v[0:15]
	s_nop 1
	v_max3_f32 v252, v80, v81, v82
	v_max3_f32 v252, v252, v83, v84
	v_max3_f32 v252, v252, v85, v86
	v_max3_f32 v252, v252, v87, v88
	v_max3_f32 v252, v252, v89, v90
	v_max3_f32 v252, v252, v91, v92
	v_max3_f32 v252, v252, v93, v94
	v_max_f32_e32 v252, v252, v95
	s_waitcnt lgkmcnt(1)
	v_mfma_f32_32x32x16_bf16 v[48:63], v[100:103], v[240:243], v[48:63]
	s_waitcnt lgkmcnt(0)
	v_mfma_f32_32x32x16_bf16 v[32:47], v[100:103], v[244:247], v[32:47]
	v_mfma_f32_32x32x16_bf16 v[16:31], v[108:111], v[240:243], v[16:31]
	v_mfma_f32_32x32x16_bf16 v[0:15], v[108:111], v[244:247], v[0:15]
	ds_read_b128 v[232:235], v229 offset:8192
	ds_read_b128 v[236:239], v229 offset:12288
	ds_read_b128 v[240:243], v230 offset:8192
	ds_read_b128 v[244:247], v230 offset:12288
	v_max3_f32 v253, v64, v65, v66
	v_max3_f32 v253, v253, v67, v68
	v_max3_f32 v253, v253, v69, v70
	v_max3_f32 v253, v253, v71, v72
	v_max3_f32 v253, v253, v73, v74
	v_max3_f32 v253, v253, v75, v76
	v_max3_f32 v253, v253, v77, v78
	v_max_f32_e32 v253, v253, v79
	v_cmp_lt_f32_e32 vcc, s97, v252
	s_cbranch_vccnz .Lgq_rare21

.Lgq_rare3:
	s_nop 15
	v_mov_b32_e32 v248, v252
	s_nop 1
	v_permlane32_swap_b32_e32 v252, v248
	v_max_f32_e32 v252, v252, v248
	v_max_f32_e32 v248, v252, v252
	v_max_f32_e32 v248, 0, v248
	v_add_f32_e32 v231, v231, v248
	v_sub_f32_e32 v80, v80, v248
	v_sub_f32_e32 v81, v81, v248
	v_sub_f32_e32 v82, v82, v248
	v_sub_f32_e32 v83, v83, v248
	v_sub_f32_e32 v84, v84, v248
	v_sub_f32_e32 v85, v85, v248
	v_sub_f32_e32 v86, v86, v248
	v_sub_f32_e32 v87, v87, v248
	v_sub_f32_e32 v88, v88, v248
	v_sub_f32_e32 v89, v89, v248
	v_sub_f32_e32 v90, v90, v248
	v_sub_f32_e32 v91, v91, v248
	v_sub_f32_e32 v92, v92, v248
	v_sub_f32_e32 v93, v93, v248
	v_sub_f32_e32 v94, v94, v248
	v_sub_f32_e32 v95, v95, v248
	v_exp_f32_e64 v249, -v248
	s_nop 0
	ds_write_b32 v222, v249
	ds_read_b128 v[198:201], v221
	ds_read_b128 v[202:205], v221 offset:32
	ds_read_b128 v[206:209], v221 offset:64
	ds_read_b128 v[210:213], v221 offset:96
	v_mul_f32_e32 v250, v250, v249
	s_waitcnt lgkmcnt(0)
	v_pk_mul_f32 v[48:49], v[48:49], v[198:199]
	v_pk_mul_f32 v[50:51], v[50:51], v[200:201]
	v_pk_mul_f32 v[52:53], v[52:53], v[202:203]
	v_pk_mul_f32 v[54:55], v[54:55], v[204:205]
	v_pk_mul_f32 v[56:57], v[56:57], v[206:207]
	v_pk_mul_f32 v[58:59], v[58:59], v[208:209]
	v_pk_mul_f32 v[60:61], v[60:61], v[210:211]
	v_pk_mul_f32 v[62:63], v[62:63], v[212:213]
	v_pk_mul_f32 v[32:33], v[32:33], v[198:199]
	v_pk_mul_f32 v[34:35], v[34:35], v[200:201]
	v_pk_mul_f32 v[36:37], v[36:37], v[202:203]
	v_pk_mul_f32 v[38:39], v[38:39], v[204:205]
	v_pk_mul_f32 v[40:41], v[40:41], v[206:207]
	v_pk_mul_f32 v[42:43], v[42:43], v[208:209]
	v_pk_mul_f32 v[44:45], v[44:45], v[210:211]
	v_pk_mul_f32 v[46:47], v[46:47], v[212:213]
	v_xor_b32_e32 v152, 0x80000000, v231
	v_mov_b32_e32 v153, v152
	v_mov_b32_e32 v154, v152
	v_mov_b32_e32 v155, v152
	v_mov_b32_e32 v156, v152
	v_mov_b32_e32 v157, v152
	v_mov_b32_e32 v158, v152
	v_mov_b32_e32 v159, v152
	v_mov_b32_e32 v160, v152
	v_mov_b32_e32 v161, v152
	v_mov_b32_e32 v162, v152
	v_mov_b32_e32 v163, v152
	v_mov_b32_e32 v164, v152
	v_mov_b32_e32 v165, v152
	v_mov_b32_e32 v166, v152
	v_mov_b32_e32 v167, v152
	s_branch .Lgq_back2
.Lgq_rare5:
	s_nop 15
	v_mov_b32_e32 v248, v253
	s_nop 1
	v_permlane32_swap_b32_e32 v253, v248
	v_max_f32_e32 v253, v253, v248
	v_max_f32_e32 v248, v253, v253
	v_max_f32_e32 v248, 0, v248
	v_add_f32_e32 v223, v223, v248
	v_sub_f32_e32 v64, v64, v248
	v_sub_f32_e32 v65, v65, v248
	v_sub_f32_e32 v66, v66, v248
	v_sub_f32_e32 v67, v67, v248
	v_sub_f32_e32 v68, v68, v248
	v_sub_f32_e32 v69, v69, v248
	v_sub_f32_e32 v70, v70, v248
	v_sub_f32_e32 v71, v71, v248
	v_sub_f32_e32 v72, v72, v248
	v_sub_f32_e32 v73, v73, v248
	v_sub_f32_e32 v74, v74, v248
	v_sub_f32_e32 v75, v75, v248
	v_sub_f32_e32 v76, v76, v248
	v_sub_f32_e32 v77, v77, v248
	v_sub_f32_e32 v78, v78, v248
	v_sub_f32_e32 v79, v79, v248
	v_exp_f32_e64 v249, -v248
	s_nop 0
	ds_write_b32 v222, v249
	ds_read_b128 v[198:201], v221
	ds_read_b128 v[202:205], v221 offset:32
	ds_read_b128 v[206:209], v221 offset:64
	ds_read_b128 v[210:213], v221 offset:96
	v_mul_f32_e32 v251, v251, v249
	s_waitcnt lgkmcnt(0)
	v_pk_mul_f32 v[16:17], v[16:17], v[198:199]
	v_pk_mul_f32 v[18:19], v[18:19], v[200:201]
	v_pk_mul_f32 v[20:21], v[20:21], v[202:203]
	v_pk_mul_f32 v[22:23], v[22:23], v[204:205]
	v_pk_mul_f32 v[24:25], v[24:25], v[206:207]
	v_pk_mul_f32 v[26:27], v[26:27], v[208:209]
	v_pk_mul_f32 v[28:29], v[28:29], v[210:211]
	v_pk_mul_f32 v[30:31], v[30:31], v[212:213]
	v_pk_mul_f32 v[0:1], v[0:1], v[198:199]
	v_pk_mul_f32 v[2:3], v[2:3], v[200:201]
	v_pk_mul_f32 v[4:5], v[4:5], v[202:203]
	v_pk_mul_f32 v[6:7], v[6:7], v[204:205]
	v_pk_mul_f32 v[8:9], v[8:9], v[206:207]
	v_pk_mul_f32 v[10:11], v[10:11], v[208:209]
	v_pk_mul_f32 v[12:13], v[12:13], v[210:211]
	v_pk_mul_f32 v[14:15], v[14:15], v[212:213]
	v_xor_b32_e32 v168, 0x80000000, v223
	v_mov_b32_e32 v169, v168
	v_mov_b32_e32 v170, v168
	v_mov_b32_e32 v171, v168
	v_mov_b32_e32 v172, v168
	v_mov_b32_e32 v173, v168
	v_mov_b32_e32 v174, v168
	v_mov_b32_e32 v175, v168
	v_mov_b32_e32 v176, v168
	v_mov_b32_e32 v177, v168
	v_mov_b32_e32 v178, v168
	v_mov_b32_e32 v179, v168
	v_mov_b32_e32 v180, v168
	v_mov_b32_e32 v181, v168
	v_mov_b32_e32 v182, v168
	v_mov_b32_e32 v183, v168
	s_branch .Lgq_back4
.Lgq_rare8:
	s_nop 15
	v_mov_b32_e32 v248, v252
	s_nop 1
	v_permlane32_swap_b32_e32 v252, v248
	v_max_f32_e32 v252, v252, v248
	v_max_f32_e32 v248, v252, v252
	v_max_f32_e32 v248, 0, v248
	v_add_f32_e32 v231, v231, v248
	v_sub_f32_e32 v80, v80, v248
	v_sub_f32_e32 v81, v81, v248
	v_sub_f32_e32 v82, v82, v248
	v_sub_f32_e32 v83, v83, v248
	v_sub_f32_e32 v84, v84, v248
	v_sub_f32_e32 v85, v85, v248
	v_sub_f32_e32 v86, v86, v248
	v_sub_f32_e32 v87, v87, v248
	v_sub_f32_e32 v88, v88, v248
	v_sub_f32_e32 v89, v89, v248
	v_sub_f32_e32 v90, v90, v248
	v_sub_f32_e32 v91, v91, v248
	v_sub_f32_e32 v92, v92, v248
	v_sub_f32_e32 v93, v93, v248
	v_sub_f32_e32 v94, v94, v248
	v_sub_f32_e32 v95, v95, v248
	v_exp_f32_e64 v249, -v248
	s_nop 0
	ds_write_b32 v222, v249
	ds_read_b128 v[96:99], v221
	ds_read_b128 v[100:103], v221 offset:32
	ds_read_b128 v[104:107], v221 offset:64
	ds_read_b128 v[108:111], v221 offset:96
	v_mul_f32_e32 v250, v250, v249
	s_waitcnt lgkmcnt(0)
	v_pk_mul_f32 v[48:49], v[48:49], v[96:97]
	v_pk_mul_f32 v[50:51], v[50:51], v[98:99]
	v_pk_mul_f32 v[52:53], v[52:53], v[100:101]
	v_pk_mul_f32 v[54:55], v[54:55], v[102:103]
	v_pk_mul_f32 v[56:57], v[56:57], v[104:105]
	v_pk_mul_f32 v[58:59], v[58:59], v[106:107]
	v_pk_mul_f32 v[60:61], v[60:61], v[108:109]
	v_pk_mul_f32 v[62:63], v[62:63], v[110:111]
	v_pk_mul_f32 v[32:33], v[32:33], v[96:97]
	v_pk_mul_f32 v[34:35], v[34:35], v[98:99]
	v_pk_mul_f32 v[36:37], v[36:37], v[100:101]
	v_pk_mul_f32 v[38:39], v[38:39], v[102:103]
	v_pk_mul_f32 v[40:41], v[40:41], v[104:105]
	v_pk_mul_f32 v[42:43], v[42:43], v[106:107]
	v_pk_mul_f32 v[44:45], v[44:45], v[108:109]
	v_pk_mul_f32 v[46:47], v[46:47], v[110:111]
	v_xor_b32_e32 v152, 0x80000000, v231
	v_mov_b32_e32 v153, v152
	v_mov_b32_e32 v154, v152
	v_mov_b32_e32 v155, v152
	v_mov_b32_e32 v156, v152
	v_mov_b32_e32 v157, v152
	v_mov_b32_e32 v158, v152
	v_mov_b32_e32 v159, v152
	v_mov_b32_e32 v160, v152
	v_mov_b32_e32 v161, v152
	v_mov_b32_e32 v162, v152
	v_mov_b32_e32 v163, v152
	v_mov_b32_e32 v164, v152
	v_mov_b32_e32 v165, v152
	v_mov_b32_e32 v166, v152
	v_mov_b32_e32 v167, v152
	s_branch .Lgq_back7
.Lgq_rare10:
	s_nop 15
	v_mov_b32_e32 v248, v253
	s_nop 1
	v_permlane32_swap_b32_e32 v253, v248
	v_max_f32_e32 v253, v253, v248
	v_max_f32_e32 v248, v253, v253
	v_max_f32_e32 v248, 0, v248
	v_add_f32_e32 v223, v223, v248
	v_sub_f32_e32 v64, v64, v248
	v_sub_f32_e32 v65, v65, v248
	v_sub_f32_e32 v66, v66, v248
	v_sub_f32_e32 v67, v67, v248
	v_sub_f32_e32 v68, v68, v248
	v_sub_f32_e32 v69, v69, v248
	v_sub_f32_e32 v70, v70, v248
	v_sub_f32_e32 v71, v71, v248
	v_sub_f32_e32 v72, v72, v248
	v_sub_f32_e32 v73, v73, v248
	v_sub_f32_e32 v74, v74, v248
	v_sub_f32_e32 v75, v75, v248
	v_sub_f32_e32 v76, v76, v248
	v_sub_f32_e32 v77, v77, v248
	v_sub_f32_e32 v78, v78, v248
	v_sub_f32_e32 v79, v79, v248
	v_exp_f32_e64 v249, -v248
	s_nop 0
	ds_write_b32 v222, v249
	ds_read_b128 v[96:99], v221
	ds_read_b128 v[100:103], v221 offset:32
	ds_read_b128 v[104:107], v221 offset:64
	ds_read_b128 v[108:111], v221 offset:96
	v_mul_f32_e32 v251, v251, v249
	s_waitcnt lgkmcnt(0)
	v_pk_mul_f32 v[16:17], v[16:17], v[96:97]
	v_pk_mul_f32 v[18:19], v[18:19], v[98:99]
	v_pk_mul_f32 v[20:21], v[20:21], v[100:101]
	v_pk_mul_f32 v[22:23], v[22:23], v[102:103]
	v_pk_mul_f32 v[24:25], v[24:25], v[104:105]
	v_pk_mul_f32 v[26:27], v[26:27], v[106:107]
	v_pk_mul_f32 v[28:29], v[28:29], v[108:109]
	v_pk_mul_f32 v[30:31], v[30:31], v[110:111]
	v_pk_mul_f32 v[0:1], v[0:1], v[96:97]
	v_pk_mul_f32 v[2:3], v[2:3], v[98:99]
	v_pk_mul_f32 v[4:5], v[4:5], v[100:101]
	v_pk_mul_f32 v[6:7], v[6:7], v[102:103]
	v_pk_mul_f32 v[8:9], v[8:9], v[104:105]
	v_pk_mul_f32 v[10:11], v[10:11], v[106:107]
	v_pk_mul_f32 v[12:13], v[12:13], v[108:109]
	v_pk_mul_f32 v[14:15], v[14:15], v[110:111]
	v_xor_b32_e32 v168, 0x80000000, v223
	v_mov_b32_e32 v169, v168
	v_mov_b32_e32 v170, v168
	v_mov_b32_e32 v171, v168
	v_mov_b32_e32 v172, v168
	v_mov_b32_e32 v173, v168
	v_mov_b32_e32 v174, v168
	v_mov_b32_e32 v175, v168
	v_mov_b32_e32 v176, v168
	v_mov_b32_e32 v177, v168
	v_mov_b32_e32 v178, v168
	v_mov_b32_e32 v179, v168
	v_mov_b32_e32 v180, v168
	v_mov_b32_e32 v181, v168
	v_mov_b32_e32 v182, v168
	v_mov_b32_e32 v183, v168
	s_branch .Lgq_back9
